# A/B: static s_setprio 1 for waves 4-7 for the whole kernel, no per-segment priority flips in the K-loops
# baseline (speedup 1.0000x reference)
; #define LAS __attribute__((address_space(3)))
; __device__ __forceinline__ unsigned pk2(float lo, float hi) { return pg8::cvt_pk_bf16(lo, hi); }
; #define LDS_WAIT() asm volatile("s_waitcnt lgkmcnt(0)" ::: "memory")
; __device__ __forceinline__ void tr_item(const float* W, int N, bf16* WT, int ldt, int drow0, const float* gain, LAS float* scr, int k0, int n0, int lane) {
;     float v[32];
; #pragma unroll
;     for (int i = 0; i < 32; ++i) { const int kk = 2 * i + (lane >> 5); v[i] = __builtin_nontemporal_load(&W[(size_t)(k0 + kk) * N + n0 + (lane & 31)]); }
; #pragma unroll
;     for (int i = 0; i < 32; ++i) { const int kk = 2 * i + (lane >> 5); scr[kk * 33 + (lane & 31)] = v[i]; }
;     LDS_WAIT(); asm volatile("" ::: "memory");
;     const int c = lane & 7;
;     f32x4 g0 = (f32x4){1.f, 1.f, 1.f, 1.f}, g1 = g0;
;     if (gain) { g0 = *(const f32x4*)(gain + k0 + 8 * c); g1 = *(const f32x4*)(gain + k0 + 8 * c + 4); }
; #pragma unroll
;     for (int j = 0; j < 4; ++j) { const int n = (lane >> 3) + 8 * j; const LAS float* s = scr + (8 * c) * 33 + n;
;         v4u o; o.x = pk2(s[0 * 33] * g0[0], s[1 * 33] * g0[1]); o.y = pk2(s[2 * 33] * g0[2], s[3 * 33] * g0[3]); o.z = pk2(s[4 * 33] * g1[0], s[5 * 33] * g1[1]); o.w = pk2(s[6 * 33] * g1[2], s[7 * 33] * g1[3]);
; __device__ __forceinline__ void prologue(CArgs* a, LAS unsigned char* lds, int gw, int NGW, int wave, int lane) {
;     asm volatile("" : "+v"(lane));
;     unsigned char* ws = a->ws + a->ws_off;
;     LAS float* scr = (LAS float*)(lds + wave * 16384);
;     constexpr int I_UP = (D / 64) * (N_UP / 32), I_DN = (FF / 64) * (D / 32), I_ABI = (D / 64) * (N_AB / 32), I_ABO = (512 / 64) * (D / 32), I_SGI = (D / 64) * (N_SGU / 32), I_SGO = (D / 64) * (D / 32);
;     constexpr int NITEMS = 4 * I_UP + 4 * I_DN + I_ABI + I_ABO + I_SGI + I_SGO;
;     for (int it = gw; it < NITEMS; it += NGW) {
;         int r = it;
;         if (r < 4 * I_UP) { const int s = r / I_UP, q = r % I_UP, l = s >> 1, f = s & 1; const int nblk = N_UP / 32, k0 = 64 * (q / nblk), n0 = 32 * (q % nblk);
.LBB0_5:
	s_or_b64 exec, exec, s[0:1]
	s_mov_b64 s[12:13], s[92:93]
	s_load_dwordx4 s[8:11], s[12:13], 0xc8
	s_lshr_b32 s48, s47, 6
	s_cmp_ge_u32 s48, 4
	s_cbranch_scc0 .Lprio_skip
	s_setprio 1
.Lprio_skip:
	s_lshl_b32 s0, s96, 3
	s_add_i32 s90, s48, s0
	v_writelane_b32 v252, s14, 4
	s_lshl_b32 s88, s14, 3
	v_and_b32_e32 v144, 63, v145
	v_writelane_b32 v252, s15, 5
	s_waitcnt lgkmcnt(0)
	s_add_u32 s14, s8, s10
	s_addc_u32 s15, s9, s11
	s_cmpk_gt_i32 s90, 0x4bff
	v_mov_b32_e32 v10, v144
	s_cbranch_scc1 .LBB0_37
	s_lshl_b32 s2, s48, 14
	v_and_b32_e32 v2, 31, v10
	v_ashrrev_i32_e32 v1, 5, v10
	v_lshl_or_b32 v4, v2, 2, s2
	s_movk_i32 s0, 0x84
	v_and_b32_e32 v3, 7, v10
	v_mov_b32_e32 v13, 0
	v_mad_u64_u32 v[14:15], s[0:1], v1, s0, v[4:5]
	v_mul_u32_u24_e32 v4, 0x420, v3
	v_lshlrev_b32_e32 v12, 4, v3
	v_or_b32_e32 v6, s2, v4
	v_lshl_add_u64 v[4:5], s[14:15], 0, v[12:13]
	s_mov_b64 s[0:1], 0x10b00000
	v_lshl_add_u64 v[18:19], v[4:5], 0, s[0:1]
	s_mov_b64 s[0:1], 0x10700000
	s_add_u32 s18, s14, 0xec00000
	v_lshl_add_u64 v[20:21], v[4:5], 0, s[0:1]
	s_mov_b64 s[0:1], 0x10500000
	s_addc_u32 s19, s15, 0
	v_lshl_add_u64 v[22:23], v[4:5], 0, s[0:1]
	s_add_u32 s20, s14, 0xc000000
	s_mov_b64 s[0:1], 0x10200000
	v_lshlrev_b32_e32 v16, 3, v3
	v_ashrrev_i32_e32 v11, 3, v10
	s_addc_u32 s21, s15, 0
	v_lshl_add_u64 v[24:25], v[4:5], 0, s[0:1]
	s_lshl_b32 s0, s90, 1
	v_lshl_add_u32 v15, v11, 2, v6
	v_add_u32_e32 v17, 8, v11
	v_add_u32_e32 v28, 16, v11
	v_add_u32_e32 v29, 24, v11
	v_add_u32_e32 v30, 0x200, v1
	s_add_i32 s22, s0, 0x7fff6c00
	s_lshl_b32 s23, s88, 1
	s_lshl_b32 s24, s90, 5
	s_lshl_b32 s25, s88, 5
	s_mov_b32 s7, 0
	s_movk_i32 s26, 0x2000
	s_movk_i32 s27, 0x4000
	s_movk_i32 s28, 0x6000
	s_mov_b32 s29, 0x8000
	s_mov_b32 s30, 0xa000
	s_mov_b32 s31, 0xc000
	s_mov_b32 s33, 0xe000
	s_mov_b32 s34, 0x10000
	s_mov_b32 s35, 0x12000
	s_mov_b32 s36, 0x14000
	s_mov_b32 s37, 0x16000
	s_mov_b32 s38, 0x18000
	s_mov_b32 s39, 0x1a000
	s_mov_b32 s40, 0x1c000
	s_mov_b32 s41, 0x1e000
	s_mov_b32 s42, 0x20000
	s_mov_b32 s43, 0x22000
	s_mov_b32 s44, 0x24000
	s_mov_b32 s45, 0x26000
	s_mov_b32 s49, 0x28000
	s_mov_b32 s50, 0x2a000
	s_mov_b32 s51, 0x2c000
	s_mov_b32 s52, 0x2e000
	s_mov_b32 s53, 0x30000
	s_mov_b32 s54, 0x32000
	s_mov_b32 s55, 0x34000
	s_mov_b32 s56, 0x36000
	s_mov_b32 s57, 0x38000
	s_mov_b32 s58, 0x3a000
	s_mov_b32 s59, 0x3c000
	s_mov_b32 s60, 0x3e000
	s_mov_b32 s61, 0x40000
	s_mov_b32 s62, 0x44000
	s_mov_b32 s63, 0x48000
	s_mov_b32 s64, 0x4c000
	s_mov_b32 s65, 0x50000
	s_mov_b32 s66, 0x54000
	s_mov_b32 s67, 0x58000
	s_mov_b32 s68, 0x5c000
	s_mov_b32 s69, 0x60000
	s_mov_b32 s70, 0x64000
	s_mov_b32 s71, 0x68000
	s_mov_b32 s72, 0x6c000
	s_mov_b32 s73, 0x70000
	s_mov_b32 s74, 0x74000
	s_mov_b32 s75, 0x78000
	s_mov_b32 s76, 0x7c000
	s_mov_b64 s[16:17], 0x1000
	s_movk_i32 s77, 0x1000
	s_movk_i32 s78, 0x1800
	s_movk_i32 s79, 0x1600
	s_movk_i32 s80, 0x5800
	v_lshlrev_b32_e32 v12, 2, v2
	v_add_u32_e32 v31, 0x400, v14
	v_add_u32_e32 v32, 0x800, v14
	v_add_u32_e32 v33, 0xc00, v14
	v_add_u32_e32 v34, 0x1000, v14
	v_add_u32_e32 v35, 0x1400, v14
	v_add_u32_e32 v36, 0x1800, v14
	v_add_u32_e32 v37, 0x1c00, v14
	v_lshlrev_b32_e32 v26, 2, v16
	s_mov_b32 s81, s90
	s_branch .LBB0_10
